# s10 + p5_ssq_preload: P5 requests the row tile's sum-of-squares before the first K-loop instead of inside the first epilogue
# speedup vs baseline: 1.0071x; 1.0071x over previous
.LBB0_586:
	s_or_b64 exec, exec, s[0:1]
	s_cmpk_gt_i32 s2, 0x3ff
	v_readfirstlane_b32 s5, v216
	s_waitcnt vmcnt(0) lgkmcnt(0)
	s_barrier
	s_cbranch_scc1 .LBB0_612
	v_lshrrev_b32_e32 v2, 1, v216
	v_lshrrev_b32_e32 v3, 5, v216
	v_and_b32_e32 v2, 24, v2
	v_and_b32_e32 v3, 4, v3
	v_bfe_u32 v4, v216, 2, 2
	v_lshlrev_b32_e32 v0, 4, v216
	v_and_b32_e32 v1, 32, v216
	v_bfe_u32 v10, v216, 2, 4
	v_or3_b32 v2, v3, v4, v2
	v_lshrrev_b32_e32 v3, 3, v216
	s_movk_i32 s0, 0x70
	v_bitop3_b32 v8, v0, v1, 48 bitop3:0x6c
	v_and_b32_e32 v9, 64, v216
	v_and_or_b32 v4, v3, s0, v10
	s_movk_i32 s0, 0x60
	v_add_u32_e32 v11, 0x2000, v0
	v_or_b32_e32 v1, v8, v9
	v_and_or_b32 v3, v3, s0, v2
	v_lshrrev_b32_e32 v0, 7, v11
	s_movk_i32 s0, 0xf0
	v_lshl_or_b32 v130, v3, 11, v1
	v_and_or_b32 v3, v0, s0, v10
	s_movk_i32 s0, 0xe0
	s_ashr_i32 s44, s2, 31
	v_and_or_b32 v0, v0, s0, v2
	s_lshr_b32 s0, s44, 29
	s_add_i32 s0, s2, s0
	s_and_b32 s8, s0, -8
	s_lshr_b32 s4, s5, 6
	s_sub_i32 s8, s2, s8
	s_lshr_b32 s1, s5, 8
	s_lshl_b32 s33, s4, 10
	s_lshl_b32 s9, s8, 7
	s_ashr_i32 s0, s0, 3
	s_cmp_lt_i32 s8, 0
	s_mulk_i32 s8, 0x81
	s_cselect_b32 s8, s8, s9
	s_add_i32 s0, s8, s0
	s_ashr_i32 s8, s0, 31
	s_lshr_b32 s8, s8, 25
	s_add_i32 s8, s0, s8
	s_ashr_i32 s9, s8, 7
	s_and_b32 s8, s8, 0xffffff80
	s_sub_i32 s8, s0, s8
	s_bfe_i32 s0, s8, 0x80000
	s_bfe_u32 s0, s0, 0x3000c
	s_add_i32 s10, s8, s0
	s_bfe_i32 s0, s10, 0x80000
	s_and_b32 s10, s10, 0xf8
	s_sub_i32 s8, s8, s10
	s_lshl_b32 s9, s9, 3
	s_sext_i32_i16 s0, s0
	s_sext_i32_i8 s8, s8
	s_lshr_b32 s0, s0, 3
	s_add_i32 s34, s9, s8
	s_ashr_i32 s35, s34, 31
	s_bfe_i64 s[10:11], s[0:1], 0x100000
	s_lshl_b64 s[8:9], s[34:35], 19
	s_lshl_b64 s[10:11], s[10:11], 19
	v_readlane_b32 s16, v255, 28
	v_readlane_b32 s17, v255, 29
	s_add_u32 s38, s16, s10
	s_addc_u32 s39, s17, s11
	s_mov_b32 s32, s34
	v_and_b32_e32 v250, 0xff, v216
	v_lshl_or_b32 v250, s34, 8, v250
	v_lshlrev_b32_e32 v250, 4, v250
	v_add_u32_e32 v250, 0x2800000, v250
	global_load_dwordx4 v[250:253], v250, s[80:81]
	s_add_i32 s35, s33, 0
	s_add_i32 m0, s35, 0x10000
	v_lshl_or_b32 v134, v0, 11, v1
	global_load_lds_dwordx4 v130, s[38:39]
	s_add_i32 m0, s35, 0x12000
	s_add_u32 s10, s38, 0x40000
	global_load_lds_dwordx4 v134, s[38:39]
	s_addc_u32 s11, s39, 0
	s_add_i32 m0, s35, 0x14000
	v_lshl_or_b32 v128, v4, 11, v1
	global_load_lds_dwordx4 v130, s[10:11]
	s_add_i32 m0, s35, 0x16000
	s_add_u32 s36, s12, s8
	s_addc_u32 s37, s13, s9
	s_add_i32 s45, s35, 0x2000
	global_load_lds_dwordx4 v134, s[10:11]
	s_mov_b32 m0, s35
	s_add_u32 s8, s36, 0x40000
	v_lshl_or_b32 v132, v3, 11, v1
	global_load_lds_dwordx4 v128, s[36:37]
	s_mov_b32 m0, s45
	s_addc_u32 s9, s37, 0
	s_add_i32 s46, s35, 0x4000
	global_load_lds_dwordx4 v132, s[36:37]
	s_mov_b32 m0, s46
	s_add_i32 s47, s35, 0x6000
	global_load_lds_dwordx4 v128, s[8:9]
	s_mov_b32 m0, s47
	v_mov_b32_e32 v131, 0
	global_load_lds_dwordx4 v132, s[8:9]
	v_mov_b32_e32 v135, v131
	v_mov_b32_e32 v129, v131
	v_mov_b32_e32 v133, v131
	s_cmp_eq_u32 s1, 1
	s_mov_b32 s17, 0
	v_lshl_add_u64 v[6:7], s[38:39], 0, v[130:131]
	v_lshl_add_u64 v[4:5], s[38:39], 0, v[134:135]
	v_lshl_add_u64 v[0:1], s[36:37], 0, v[128:129]
	s_cselect_b64 s[18:19], -1, 0
	s_cmp_lg_u32 s1, 1
	v_lshl_add_u64 v[2:3], s[36:37], 0, v[132:133]
	s_cbranch_scc1 .LBB0_589
	s_barrier

.LBB0_602:
	v_mov_b32_e32 v144, s53
	ds_read_b32 v144, v144
	s_waitcnt lgkmcnt(0)
	v_cmp_eq_u32_e32 vcc, s34, v144
	s_cbranch_vccnz .LBB0_608
	s_barrier
	s_and_saveexec_b64 s[36:37], s[0:1]
	s_cbranch_execz .LBB0_605
	s_cmp_eq_u32 s34, s32
	s_cbranch_scc1 .Lp5_pre
	v_lshl_or_b32 v144, s34, 8, v216
	v_ashrrev_i32_e32 v145, 31, v144
	v_lshl_add_u64 v[144:145], v[144:145], 4, s[14:15]
	global_load_dwordx4 v[144:147], v[144:145], off
	s_waitcnt vmcnt(0)
	s_branch .Lp5_have
.Lp5_pre:
	s_waitcnt vmcnt(0)
	v_mov_b32_e32 v144, v250
	v_mov_b32_e32 v145, v251
	v_mov_b32_e32 v146, v252
	v_mov_b32_e32 v147, v253
.Lp5_have:
	v_mov_b32_e32 v178, v145
	v_mov_b32_e32 v179, v146
	v_mov_b32_e32 v145, v147
	v_pk_add_f32 v[144:145], v[178:179], v[144:145]
	s_nop 0
	v_add_f32_e32 v144, v144, v145
	v_fmamk_f32 v144, v144, 0x3a800000, v176
	v_mul_f32_e32 v145, 0x4b800000, v144
	v_cmp_gt_f32_e32 vcc, s54, v144
	s_nop 1
	v_cndmask_b32_e32 v144, v144, v145, vcc
	v_rsq_f32_e32 v144, v144
	s_nop 0
	v_mul_f32_e32 v145, 0x45800000, v144
	v_cndmask_b32_e32 v144, v144, v145, vcc
	ds_write_b32 v153, v144
